# mixer schedule: pool-type sample jobs on workgroups 224-255, RG-LRU-type sample jobs on workgroups 0-63
# baseline (speedup 1.0000x reference)
.Lsch_c5:
	s_lshr_b32 s25, s2, 3
	s_mul_i32 s25, s25, 12
	s_and_b32 s26, s2, 7
	s_add_i32 s25, s25, s26
	s_add_i32 s25, s25, 0x604
	s_cmp_eq_u32 s22, 5
	s_cselect_b32 s25, s25, 0x660
	s_branch .Lsch_keep

.Lsch_s5:
	s_sub_i32 s26, s2, 0xe0
	s_lshr_b32 s25, s26, 2
	s_mul_i32 s25, s25, 12
	s_and_b32 s26, s26, 3
	s_add_i32 s25, s25, s26
	s_add_i32 s25, s25, 0x600
	s_cmp_eq_u32 s22, 5
	s_cselect_b32 s25, s25, 0x660
